# OUT tail entry: store-drain vmcnt(0) dropped (stores acknowledged under the prologue's DMA round trip)
# baseline (speedup 1.0000x reference)
; #define PG8_WAIT_V(n) asm volatile("s_waitcnt vmcnt(" #n ")" ::: "memory")
; #define PG8_BAR __builtin_amdgcn_s_barrier()
; template <class Epi, bool ALIGN_EPI, bool SP2, bool BF = false, bool HALFM = false, class Order = StaticOrder>
; __device__ __forceinline__ void gemm_phase(LAS unsigned char* lds, const int tid, const Gemm g, const Order& S, const Epi& E, const bool dry = false) {
;     ...
;     PG8_WAIT_V(0);
;     if constexpr (!ALIGN_EPI) { if (wr == 0) PG8_BAR; }
;     PG8_BAR;
; __device__ __forceinline__ void ph_outproj(Frame& F, int l, float gscale, bool dry) {
;     ...
;     pg8::gemm_phase<EpiOut, true, true>(F.lds, F.tid, g, S, E, dry);
;     if (split) { pg8::HalfOrder H{S, nfull}; EpiOut E2 = E; E2.half = true; pg8::gemm_phase<EpiOut, true, true, false, true, pg8::HalfOrder>(F.lds, F.tid, g, H, E2, false); }
.LBB0_498:
	s_nop 0
	v_readlane_b32 s82, v252, 50
	v_readlane_b32 s84, v252, 52
	v_readlane_b32 s54, v253, 8
	v_readlane_b32 s14, v253, 5
	v_readlane_b32 s86, v252, 44
	v_readlane_b32 s80, v252, 45
	v_readlane_b32 s76, v252, 46
	v_readlane_b32 s77, v252, 47
	v_readlane_b32 s78, v252, 48
	v_readlane_b32 s79, v252, 49
	v_readlane_b32 s83, v252, 51
	v_readlane_b32 s85, v252, 53
	s_movk_i32 s87, 0x100
	s_mov_b32 s81, s64
	v_readlane_b32 s55, v253, 9
	s_mov_b32 s11, s67
	v_readlane_b32 s15, v253, 6
	s_barrier
